# dilated phase 10: rotate item dealing within each XCD group per round so every workgroup gets 19 K/V stages (was 16 or 24)
# speedup vs baseline: 1.0041x; 1.0041x over previous
; DI DilItem dil_item(int k) {
;     DilItem it; int bh, sub;
;     if (k < 1024) { it.g = 0; bh = k >> 4; sub = k & 15; }
;     else { const int idx = k - 1024; bh = idx >> 5; it.g = 1 + ((idx >> 4) & 1); sub = idx & 15; }
.LBB0_1082:
	s_mov_b32 s100, s36
	s_lshr_b32 s98, s36, 8
	s_and_b32 s98, s98, 3
	s_lshr_b32 s99, s36, 10
	s_lshl_b32 s99, s99, 4
	s_add_i32 s98, s98, s99
	s_add_i32 s98, s98, s36
	s_add_i32 s98, s98, 16
	s_and_b32 s98, s98, 31
	s_andn2_b32 s36, s36, 31
	s_or_b32 s36, s36, s98
	s_cmpk_gt_i32 s36, 0x3ff
	s_mov_b64 s[28:29], -1
	s_cbranch_scc0 .LBB0_1084
	s_add_i32 s6, s36, 0xfffffc00
	s_bfe_u32 s7, s36, 0x10004
	s_lshr_b32 s6, s6, 5
	s_add_i32 s61, s7, 1
	s_mov_b64 s[28:29], 0

; DI DilItem dil_item(int k) {
;     DilItem it; int bh, sub;
;     if (k < 1024) { it.g = 0; bh = k >> 4; sub = k & 15; }
;     else { const int idx = k - 1024; bh = idx >> 5; it.g = 1 + ((idx >> 4) & 1); sub = idx & 15; }
.LBB0_1086:
	s_add_i32 s59, s18, s100
	s_cmpk_gt_i32 s59, 0xbff
	s_cselect_b64 s[28:29], -1, 0
	s_cmpk_lt_i32 s59, 0xc00
	s_cselect_b64 s[34:35], -1, 0
	s_and_b64 s[30:31], s[34:35], exec
	s_cselect_b32 s7, s18, 0
	s_add_i32 s7, s7, s100
	s_lshr_b32 s98, s7, 8
	s_and_b32 s98, s98, 3
	s_lshr_b32 s99, s7, 10
	s_lshl_b32 s99, s99, 4
	s_add_i32 s98, s98, s99
	s_add_i32 s98, s98, s7
	s_add_i32 s98, s98, 16
	s_and_b32 s98, s98, 31
	s_andn2_b32 s7, s7, 31
	s_or_b32 s7, s7, s98
	s_cmpk_gt_i32 s7, 0x3ff
	s_mov_b64 s[30:31], -1
	s_cbranch_scc0 .LBB0_1088
	s_add_i32 s12, s7, 0xfffffc00
	s_lshr_b32 s47, s12, 5
	s_bfe_u32 s12, s7, 0x10004
	s_add_i32 s37, s12, 1
	s_mov_b64 s[30:31], 0
